# no per-phase flips + one static s_setprio 1 for waves 0-3 (older half) at kernel entry
# speedup vs baseline: 1.0096x; 1.0005x over previous
_Z10fwd_kernel6Params:
	v_readfirstlane_b32 s98, v0
	s_nop 3
	s_and_b32 s98, s98, 0x3ff
	s_cmp_lt_u32 s98, 0x100
	s_cbranch_scc0 .Lprio_skip
	s_setprio 1
